# gate-prep and final-phase rows assigned per XCD; seams in-proj -> gate-prep (odd layers) and FFN-down -> final XCD-local
# baseline (speedup 1.0000x reference)
.Lhw_bar_scope:
	v_readlane_b32 s2, v246, 26
	s_and_b32 s9, s88, 1
	s_mul_i32 s8, s9, 0x120
	s_xor_b32 s9, s9, 1
	s_lshl_b32 s9, s9, 6
	s_or_b32 s8, s8, s9
	s_or_b32 s8, s8, 0xe1e
	s_cmp_eq_u32 s96, 49
	s_cselect_b32 s9, 1, 0
	s_or_b32 s8, s8, s9
	s_lshr_b32 s8, s8, s2
	v_readlane_b32 s6, v246, 41
	s_and_b32 s8, s8, 1
	s_and_b32 s8, s8, s6
	v_writelane_b32 v246, s8, 42
	s_waitcnt vmcnt(0)
	s_barrier
	v_mov_b32 v0, v194
	s_nop 0
	v_cmp_eq_u32_e32 vcc, 0, v0
	s_and_saveexec_b64 s[0:1], vcc
	s_cbranch_execz .LBB0_108
	s_waitcnt vmcnt(0) expcnt(0) lgkmcnt(0)
	ds_read_b32 v3, v1
	ds_read_b32 v0, v1 offset:4
	s_waitcnt lgkmcnt(1)
	v_cmp_ne_u32_e32 vcc, 0, v3
	s_cbranch_vccnz .LBB0_71
	s_mov_b32 s2, 1
	s_branch .LBB0_54

.LBB0_123:
	s_ashr_i32 s0, s88, 1
	s_ashr_i32 s1, s0, 31
	s_mul_i32 s2, s88, 3
	v_writelane_b32 v246, s2, 27
	s_mul_i32 s2, s88, 5
	s_cmp_lt_i32 s96, 37
	v_writelane_b32 v246, s2, 28
	s_cselect_b64 s[8:9], -1, 0
	v_writelane_b32 v246, s8, 29
	s_ashr_i32 s89, s88, 31
	s_movk_i32 s93, 0xfff
	v_writelane_b32 v246, s9, 30
	s_movk_i32 s92, 0x2fff
	v_readlane_b32 s2, v246, 25
	s_cmp_lt_i32 s2, 6
	s_mov_b64 s[10:11], -1
	s_cbranch_scc1 .LBB0_419
	s_and_b32 s8, s88, -2
	v_readlane_b32 s2, v246, 25
	s_cmp_lt_i32 s2, 9
	s_cbranch_scc1 .LBB0_155
	v_readlane_b32 s2, v246, 25
	s_cmp_lt_i32 s2, 10
	s_cbranch_scc1 .LBB0_149
	v_readlane_b32 s2, v246, 25
	s_cmp_gt_i32 s2, 10
	s_cbranch_scc0 .LBB0_143
	v_readlane_b32 s12, v246, 16
	s_lshr_b32 s13, s83, 1
	s_lshl_b32 s12, s12, 7
	s_and_b32 s16, s83, 1
	s_add_i32 s2, s12, 0x5ff
	s_add_i32 s13, s13, s12
	v_writelane_b32 v247, s16, 31
	v_writelane_b32 v246, s2, 44
	v_writelane_b32 v247, s13, 59
	s_lshl_b32 s2, s16, 6
	v_writelane_b32 v247, s2, 55
	s_lshl_b32 s2, s16, 8
	s_lshl_b32 s12, s13, 9
	s_or_b32 s12, s12, s2
	v_writelane_b32 v247, s12, 50
	s_add_i32 s12, s12, 0x4000
	v_writelane_b32 v247, s12, 51
	s_lshl_b32 s12, s13, 5
	v_writelane_b32 v247, s12, 60
	s_mov_b32 s12, 64
	v_writelane_b32 v247, s12, 43
	s_mov_b32 s12, 0x10000
	v_writelane_b32 v247, s12, 56
	s_mov_b32 s12, 0x8000
	v_writelane_b32 v247, s12, 57
	s_mov_b32 s12, 0x800
	v_writelane_b32 v247, s12, 58
	s_mov_b32 s12, 0x1000
	v_writelane_b32 v247, s12, 61
	s_mov_b32 s12, 32
	v_writelane_b32 v247, s12, 62
	s_mov_b32 s12, 0x400
	v_writelane_b32 v247, s12, 63
	v_readlane_b32 s12, v247, 29
	v_readlane_b32 s13, v247, 30
	s_mov_b64 s[10:11], s[84:85]
	s_andn2_b64 vcc, exec, s[12:13]
	v_readlane_b32 s16, v247, 62
	s_waitcnt vmcnt(0) lgkmcnt(0)
	v_mov_b32 v2, v194
	s_cbranch_vccnz .LBB0_142
	s_load_dwordx4 s[40:43], s[10:11], 0xc8
	v_readlane_b32 s2, v247, 31
	s_or_b32 s12, s8, s2
	s_ashr_i32 s13, s12, 31
	s_lshl_b64 s[14:15], s[12:13], 10
	s_lshl_b64 s[12:13], s[12:13], 14
	s_waitcnt lgkmcnt(0)
	s_add_u32 s12, s40, s12
	v_ashrrev_i32_e32 v3, 31, v2
	s_addc_u32 s13, s41, s13
	v_lshlrev_b64 v[2:3], 2, v[2:3]
	v_lshl_add_u64 v[4:5], s[12:13], 0, v[2:3]
	s_movk_i32 s2, 0x1000
	v_add_co_u32_e32 v6, vcc, s2, v4
	s_movk_i32 s2, 0x2000
	s_nop 0
	v_addc_co_u32_e32 v7, vcc, 0, v5, vcc
	s_add_u32 s12, s42, s14
	v_add_co_u32_e32 v8, vcc, s2, v4
	s_addc_u32 s13, s43, s15
	s_nop 0
	v_addc_co_u32_e32 v9, vcc, 0, v5, vcc
	v_lshl_add_u64 v[10:11], s[12:13], 0, v[2:3]
	s_movk_i32 s2, 0x3000
	global_load_dword v0, v[10:11], off
	v_add_co_u32_e32 v10, vcc, s2, v4
	s_load_dwordx2 s[10:11], s[10:11], 0x108
	s_nop 0
	v_addc_co_u32_e32 v11, vcc, 0, v5, vcc
	global_load_dword v78, v[8:9], off offset:-4096
	global_load_dword v66, v[8:9], off offset:2048
	global_load_dword v69, v[8:9], off offset:1024
	global_load_dword v68, v[8:9], off
	global_load_dword v71, v[10:11], off offset:3072
	global_load_dword v70, v[10:11], off offset:2048
	global_load_dword v73, v[10:11], off offset:1024
	global_load_dword v72, v[10:11], off
	global_load_dword v67, v[8:9], off offset:3072
	global_load_dword v79, v[4:5], off
	global_load_dword v80, v[4:5], off offset:1024
	global_load_dword v81, v[4:5], off offset:2048
	global_load_dword v82, v[4:5], off offset:3072
	global_load_dword v83, v[6:7], off offset:1024
	global_load_dword v75, v[6:7], off offset:3072
	global_load_dword v74, v[6:7], off offset:2048
	v_readlane_b32 s2, v247, 55
	s_waitcnt lgkmcnt(0)
	s_add_u32 s2, s10, s2
	s_addc_u32 s9, s11, 0
	v_lshl_add_u64 v[2:3], s[10:11], 0, v[2:3]
	s_mov_b64 s[10:11], 0x1aad8100
	s_add_u32 s6, s2, 0x1a958100
	v_lshl_add_u64 v[76:77], v[2:3], 0, s[10:11]
	v_readlane_b32 s2, v247, 51
	v_readlane_b32 s11, v247, 50
	s_addc_u32 s9, s9, 0
	s_mov_b32 s10, s2
	v_readlane_b32 s2, v247, 60
	s_mov_b32 s12, s11
	v_readlane_b32 s11, v247, 59
	s_branch .LBB0_130
.LBB0_129:
	v_readlane_b32 s11, v247, 43
	s_add_i32 s11, s20, s11
	v_readlane_b32 s16, v247, 62
	v_readlane_b32 s13, v247, 56
	v_readlane_b32 s14, v247, 61
	s_add_i32 s11, s11, s16
	s_add_i32 s12, s12, s13
	s_add_i32 s2, s2, s14
	s_add_i32 s10, s10, s13
	v_readlane_b32 s13, v246, 44
	s_nop 0
	s_cmp_gt_u32 s11, s13
	s_cbranch_scc1 .LBB0_142

.LBB0_149:
	s_andn2_b64 vcc, exec, s[10:11]
	s_cbranch_vccnz .LBB0_154
	s_mov_b64 s[10:11], s[84:85]
	v_mov_b32 v0, v194
	v_readlane_b32 s2, v246, 16
	s_lshl_b32 s6, s83, 2
	s_lshl_b32 s2, s2, 7
	s_add_i32 s2, s2, s6
	s_waitcnt vmcnt(0) lgkmcnt(0)
	v_ashrrev_i32_e32 v2, 6, v0
	v_add_u32_e32 v2, s2, v2
	s_movk_i32 s2, 0x3000
	v_cmp_gt_i32_e32 vcc, s2, v2
	s_and_saveexec_b64 s[12:13], vcc
	s_movk_i32 s18, 0x100
	v_readlane_b32 s2, v246, 16
	s_lshl_b32 s2, s2, 7
	s_add_i32 s2, s2, 0x5ff
	s_mov_b32 s6, 0x800000
	v_readlane_b32 s19, v247, 54
	s_cbranch_execz .LBB0_153
	s_load_dwordx2 s[16:17], s[10:11], 0x108
	v_lshlrev_b32_e32 v0, 2, v0
	v_and_b32_e32 v0, 0xfc, v0
	v_mov_b32_e32 v5, v1
	v_lshlrev_b32_e32 v4, 2, v0
	s_waitcnt lgkmcnt(0)
	s_add_u32 s14, s16, 0x7b00000
	s_addc_u32 s15, s17, 0
	v_lshl_add_u64 v[4:5], s[16:17], 0, v[4:5]
	s_mov_b64 s[16:17], 0
	v_lshlrev_b32_e32 v0, 2, v0
